# hipcc's 64-iteration scalar wave-reduction loops in front of the one-lane atomics (seam arrive, unit dequeue, hand-off counters) replaced by the constant sum 1
# speedup vs baseline: 1.0274x; 1.0210x over previous
.LBB0_37:
	s_add_i32 s4, s4, 1
	s_mov_b64 s[2:3], 0
	v_mbcnt_lo_u32_b32 v2, exec_lo, 0
	v_mbcnt_hi_u32_b32 v2, exec_hi, v2
	v_cmp_eq_u32_e32 vcc, 0, v2
	s_and_saveexec_b64 s[2:3], vcc
	s_xor_b64 s[2:3], exec, s[2:3]
	s_cbranch_execz .LBB0_40
	v_mov_b32_e32 v2, 0
	v_mov_b32_e32 v3, s4
	global_atomic_add v2, v3, s[18:19]

.LBB0_273:
	s_add_i32 s8, s8, 1
	s_mov_b64 s[6:7], 0
	v_mbcnt_lo_u32_b32 v1, exec_lo, 0
	v_mbcnt_hi_u32_b32 v1, exec_hi, v1
	v_cmp_eq_u32_e32 vcc, 0, v1
	s_and_saveexec_b64 s[6:7], vcc
	s_xor_b64 s[6:7], exec, s[6:7]
	s_cbranch_execz .LBB0_276
	v_mov_b32_e32 v1, 0
	v_mov_b32_e32 v2, s8
	global_atomic_add v1, v2, s[4:5]

.LBB0_291:
	s_add_i32 s12, s12, 1
	s_mov_b64 s[10:11], 0
	v_mov_b32_e32 v0, 0
	v_mbcnt_lo_u32_b32 v1, exec_lo, 0
	v_mbcnt_hi_u32_b32 v1, exec_hi, v1
	v_cmp_eq_u32_e32 vcc, 0, v1
	s_and_saveexec_b64 s[10:11], vcc
	s_xor_b64 s[10:11], exec, s[10:11]
	s_cbranch_execz .LBB0_294
	v_mov_b32_e32 v1, s12
	global_atomic_add v1, v149, v1, s[38:39] offset:1280 sc0

.LBB0_386:
	s_add_i32 s14, s14, 1
	s_mov_b64 s[10:11], 0
	v_mbcnt_lo_u32_b32 v0, exec_lo, 0
	v_mbcnt_hi_u32_b32 v0, exec_hi, v0
	v_cmp_eq_u32_e32 vcc, 0, v0
	s_and_saveexec_b64 s[10:11], vcc
	s_xor_b64 s[10:11], exec, s[10:11]
	s_cbranch_execz .LBB0_389
	v_mov_b32_e32 v0, s14
	global_atomic_add v149, v0, s[38:39] offset:1792

.LBB0_406:
	s_add_i32 s12, s12, 1
	s_mov_b64 s[10:11], 0
	v_mbcnt_lo_u32_b32 v0, exec_lo, 0
	v_mbcnt_hi_u32_b32 v0, exec_hi, v0
	v_cmp_eq_u32_e32 vcc, 0, v0
	s_and_saveexec_b64 s[10:11], vcc
	s_xor_b64 s[10:11], exec, s[10:11]
	s_cbranch_execz .LBB0_286
	v_mov_b32_e32 v0, s12
	global_atomic_add v149, v0, s[38:39] offset:1536
	s_branch .LBB0_286

.LBB0_552:
	s_add_i32 s20, s20, 1
	s_mov_b64 s[2:3], 0
	v_mbcnt_lo_u32_b32 v0, exec_lo, 0
	v_mbcnt_hi_u32_b32 v0, exec_hi, v0
	v_cmp_eq_u32_e32 vcc, 0, v0
	s_and_saveexec_b64 s[2:3], vcc
	s_xor_b64 s[2:3], exec, s[2:3]
	s_cbranch_execz .LBB0_555
	v_mov_b32_e32 v0, 0
	v_mov_b32_e32 v1, s20
	global_atomic_add v0, v1, s[38:39] offset:256

.LBB0_572:
	s_add_i32 s24, s24, 1
	s_mov_b64 s[22:23], 0
	v_mbcnt_lo_u32_b32 v0, exec_lo, 0
	v_mbcnt_hi_u32_b32 v0, exec_hi, v0
	v_cmp_eq_u32_e32 vcc, 0, v0
	s_and_saveexec_b64 s[22:23], vcc
	s_xor_b64 s[22:23], exec, s[22:23]
	s_cbranch_execz .LBB0_575
	v_mov_b32_e32 v0, 0
	v_mov_b32_e32 v1, s24
	global_atomic_add v0, v1, s[20:21]

.LBB0_631:
	s_add_i32 s10, s10, 1
	s_mov_b64 s[6:7], 0
	v_mbcnt_lo_u32_b32 v1, exec_lo, 0
	v_mbcnt_hi_u32_b32 v1, exec_hi, v1
	v_cmp_eq_u32_e32 vcc, 0, v1
	s_and_saveexec_b64 s[6:7], vcc
	s_xor_b64 s[6:7], exec, s[6:7]
	s_cbranch_execz .LBB0_634
	v_mov_b32_e32 v1, 0
	v_mov_b32_e32 v2, s10
	global_atomic_add v1, v2, s[4:5]

.LBB0_926:
	s_add_i32 s6, s6, 1
	s_mov_b64 s[4:5], 0
	v_mov_b32_e32 v0, 0
	v_mbcnt_lo_u32_b32 v2, exec_lo, 0
	v_mbcnt_hi_u32_b32 v2, exec_hi, v2
	v_cmp_eq_u32_e32 vcc, 0, v2
	s_and_saveexec_b64 s[4:5], vcc
	s_xor_b64 s[4:5], exec, s[4:5]
	s_cbranch_execz .LBB0_929
	v_mov_b32_e32 v2, s6
	global_atomic_add v2, v1, v2, s[38:39] sc0

.LBB0_1026:
	s_add_i32 s6, s6, 1
	s_mov_b64 s[4:5], 0
	v_mbcnt_lo_u32_b32 v0, exec_lo, 0
	v_mbcnt_hi_u32_b32 v0, exec_hi, v0
	v_cmp_eq_u32_e32 vcc, 0, v0
	s_and_saveexec_b64 s[4:5], vcc
	s_xor_b64 s[4:5], exec, s[4:5]
	s_cbranch_execz .LBB0_1029
	v_mov_b32_e32 v0, s6
	global_atomic_add v1, v0, s[38:39] offset:1024

.LBB0_1074:
	s_add_i32 s6, s6, 1
	s_mov_b64 s[4:5], 0
	v_mbcnt_lo_u32_b32 v0, exec_lo, 0
	v_mbcnt_hi_u32_b32 v0, exec_hi, v0
	v_cmp_eq_u32_e32 vcc, 0, v0
	s_and_saveexec_b64 s[4:5], vcc
	s_xor_b64 s[4:5], exec, s[4:5]
	s_cbranch_execz .LBB0_921
	v_mov_b32_e32 v0, s6
	global_atomic_add v1, v0, s[38:39] offset:768
	s_branch .LBB0_921

.LBB0_1273:
	s_add_i32 s20, s20, 1
	s_mov_b64 s[0:1], 0
	v_mbcnt_lo_u32_b32 v0, exec_lo, 0
	v_mbcnt_hi_u32_b32 v0, exec_hi, v0
	v_cmp_eq_u32_e32 vcc, 0, v0
	s_and_saveexec_b64 s[0:1], vcc
	s_xor_b64 s[0:1], exec, s[0:1]
	s_cbranch_execz .LBB0_1276
	v_mov_b32_e32 v0, 0
	v_mov_b32_e32 v1, s20
	global_atomic_add v0, v1, s[38:39] offset:512

.LBB0_1336:
	s_add_i32 s6, s6, 1
	s_mov_b64 s[4:5], 0
	v_mbcnt_lo_u32_b32 v1, exec_lo, 0
	v_mbcnt_hi_u32_b32 v1, exec_hi, v1
	v_cmp_eq_u32_e32 vcc, 0, v1
	s_and_saveexec_b64 s[4:5], vcc
	s_xor_b64 s[4:5], exec, s[4:5]
	s_cbranch_execz .LBB0_1339
	v_mov_b32_e32 v1, 0
	v_mov_b32_e32 v2, s6
	global_atomic_add v1, v2, s[2:3]
